# E50b: layer-1 memory-attention PROMPT units: K-fragment and transposed-V LDS reads issued through a 6-deep rolling register window ahead of the MFMAs (loop body + peeled last tile); on E41
# speedup vs baseline: 1.0047x; 1.0047x over previous
.LBB0_1319:
	v_pk_add_f32 v[16:17], v[98:99], v[158:159] op_sel_hi:[1,0] neg_lo:[0,1] neg_hi:[0,1]
	v_pk_add_f32 v[98:99], v[100:101], v[158:159] op_sel_hi:[1,0] neg_lo:[0,1] neg_hi:[0,1]
	v_add3_u32 v2, s8, v157, v170
	ds_read_b64_tr_b16 v[226:227], v2 offset:17408
	ds_read_b64_tr_b16 v[228:229], v2 offset:19968
	ds_read_b64_tr_b16 v[230:231], v2 offset:17472
	ds_read_b64_tr_b16 v[232:233], v2 offset:20032
	ds_read_b64_tr_b16 v[234:235], v2 offset:17536
	ds_read_b64_tr_b16 v[236:237], v2 offset:20096
	ds_read_b64_tr_b16 v[238:239], v2 offset:17600
	ds_read_b64_tr_b16 v[240:241], v2 offset:20160
	ds_read_b64_tr_b16 v[246:247], v2 offset:22528
	ds_read_b64_tr_b16 v[248:249], v2 offset:25088
	ds_read_b64_tr_b16 v[250:251], v2 offset:22592
	ds_read_b64_tr_b16 v[252:253], v2 offset:25152
	v_exp_f32_e32 v168, v98
	v_exp_f32_e32 v169, v99
	v_pk_add_f32 v[98:99], v[102:103], v[158:159] op_sel_hi:[1,0] neg_lo:[0,1] neg_hi:[0,1]
	v_exp_f32_e32 v16, v16
	v_exp_f32_e32 v102, v98
	v_exp_f32_e32 v103, v99
	v_pk_add_f32 v[98:99], v[104:105], v[158:159] op_sel_hi:[1,0] neg_lo:[0,1] neg_hi:[0,1]
	v_exp_f32_e32 v17, v17
	v_exp_f32_e32 v104, v98
	v_exp_f32_e32 v105, v99
	v_cvt_pk_bf16_f32 v98, v16, v17
	v_cvt_pk_bf16_f32 v99, v168, v169
	v_cvt_pk_bf16_f32 v100, v102, v103
	v_cvt_pk_bf16_f32 v101, v104, v105
	v_pk_add_f32 v[106:107], v[106:107], v[158:159] op_sel_hi:[1,0] neg_lo:[0,1] neg_hi:[0,1]
	v_pk_add_f32 v[108:109], v[108:109], v[158:159] op_sel_hi:[1,0] neg_lo:[0,1] neg_hi:[0,1]
	s_waitcnt lgkmcnt(10)
	v_mfma_f32_32x32x16_bf16 v[66:81], v[226:229], v[98:101], v[66:81]
	ds_read_b64_tr_b16 v[226:227], v2 offset:22656
	ds_read_b64_tr_b16 v[228:229], v2 offset:25216
	v_add_f32_e64 v110, v110, -v158
	v_add_f32_e64 v111, v111, -v158
	v_add_f32_e64 v112, v112, -v158
	v_add_f32_e64 v113, v113, -v158
	v_exp_f32_e32 v106, v106
	v_exp_f32_e32 v107, v107
	v_exp_f32_e32 v108, v108
	v_exp_f32_e32 v109, v109
	v_exp_f32_e32 v110, v110
	s_waitcnt lgkmcnt(10)
	v_mfma_f32_32x32x16_bf16 v[50:65], v[230:233], v[98:101], v[50:65]
	ds_read_b64_tr_b16 v[230:231], v2 offset:22720
	ds_read_b64_tr_b16 v[232:233], v2 offset:25280
	v_exp_f32_e32 v111, v111
	v_exp_f32_e32 v112, v112
	v_exp_f32_e32 v113, v113
	v_pk_add_f32 v[82:83], v[82:83], v[158:159] op_sel_hi:[1,0] neg_lo:[0,1] neg_hi:[0,1]
	v_pk_add_f32 v[84:85], v[84:85], v[158:159] op_sel_hi:[1,0] neg_lo:[0,1] neg_hi:[0,1]
	v_pk_add_f32 v[86:87], v[86:87], v[158:159] op_sel_hi:[1,0] neg_lo:[0,1] neg_hi:[0,1]
	s_waitcnt lgkmcnt(10)
	v_mfma_f32_32x32x16_bf16 v[34:49], v[234:237], v[98:101], v[34:49]
	ds_read_b64_tr_b16 v[234:235], v2 offset:27648
	ds_read_b64_tr_b16 v[236:237], v2 offset:30208
	v_add_f32_e64 v88, v88, -v158
	v_add_f32_e64 v89, v89, -v158
	v_exp_f32_e32 v82, v82
	v_exp_f32_e32 v83, v83
	v_exp_f32_e32 v84, v84
	v_exp_f32_e32 v85, v85
	v_exp_f32_e32 v86, v86
	v_exp_f32_e32 v87, v87
	s_waitcnt lgkmcnt(10)
	v_mfma_f32_32x32x16_bf16 v[18:33], v[238:241], v[98:101], v[18:33]
	ds_read_b64_tr_b16 v[238:239], v2 offset:27712
	ds_read_b64_tr_b16 v[240:241], v2 offset:30272
	v_cvt_pk_bf16_f32 v98, v106, v107
	v_cvt_pk_bf16_f32 v99, v108, v109
	v_cvt_pk_bf16_f32 v100, v110, v111
	v_cvt_pk_bf16_f32 v101, v112, v113
	v_exp_f32_e32 v88, v88
	v_exp_f32_e32 v89, v89
	s_waitcnt lgkmcnt(10)
	v_mfma_f32_32x32x16_bf16 v[66:81], v[246:249], v[98:101], v[66:81]
	ds_read_b64_tr_b16 v[246:247], v2 offset:27776
	ds_read_b64_tr_b16 v[248:249], v2 offset:30336
	v_add_f32_e64 v16, v16, 0
	v_add_f32_e64 v17, v17, 0
	v_add_f32_e64 v90, v90, -v158
	v_add_f32_e64 v91, v91, -v158
	v_pk_add_f32 v[16:17], v[168:169], v[16:17]
	v_exp_f32_e32 v208, v90
	v_exp_f32_e32 v209, v91
	v_pk_add_f32 v[90:91], v[92:93], v[158:159] op_sel_hi:[1,0] neg_lo:[0,1] neg_hi:[0,1]
	s_waitcnt lgkmcnt(10)
	v_mfma_f32_32x32x16_bf16 v[50:65], v[250:253], v[98:101], v[50:65]
	ds_read_b64_tr_b16 v[250:251], v2 offset:27840
	ds_read_b64_tr_b16 v[252:253], v2 offset:30400
	v_add_f32_e64 v16, v102, v16
	v_add_f32_e64 v17, v103, v17
	v_exp_f32_e32 v210, v90
	v_exp_f32_e32 v211, v91
	v_pk_add_f32 v[90:91], v[94:95], v[158:159] op_sel_hi:[1,0] neg_lo:[0,1] neg_hi:[0,1]
	v_pk_add_f32 v[16:17], v[104:105], v[16:17]
	s_nop 0
	v_pk_add_f32 v[16:17], v[106:107], v[16:17]
	s_waitcnt lgkmcnt(10)
	v_mfma_f32_32x32x16_bf16 v[34:49], v[226:229], v[98:101], v[34:49]
	ds_read_b64_tr_b16 v[226:227], v2 offset:32768
	ds_read_b64_tr_b16 v[228:229], v2 offset:35328
	v_add_f32_e64 v16, v108, v16
	v_add_f32_e64 v17, v109, v17
	v_add_f32_e64 v16, v110, v16
	v_add_f32_e64 v17, v111, v17
	v_add_f32_e64 v16, v112, v16
	v_add_f32_e64 v17, v113, v17
	v_pk_add_f32 v[16:17], v[82:83], v[16:17]
	s_waitcnt lgkmcnt(10)
	v_mfma_f32_32x32x16_bf16 v[18:33], v[230:233], v[98:101], v[18:33]
	ds_read_b64_tr_b16 v[230:231], v2 offset:32832
	ds_read_b64_tr_b16 v[232:233], v2 offset:35392
	v_cvt_pk_bf16_f32 v98, v82, v83
	v_cvt_pk_bf16_f32 v99, v84, v85
	v_cvt_pk_bf16_f32 v100, v86, v87
	v_cvt_pk_bf16_f32 v101, v88, v89
	v_pk_add_f32 v[16:17], v[84:85], v[16:17]
	s_waitcnt lgkmcnt(10)
	v_mfma_f32_32x32x16_bf16 v[66:81], v[234:237], v[98:101], v[66:81]
	ds_read_b64_tr_b16 v[234:235], v2 offset:32896
	ds_read_b64_tr_b16 v[236:237], v2 offset:35456
	v_add_f32_e64 v16, v86, v16
	v_add_f32_e64 v17, v87, v17
	v_add_f32_e64 v16, v88, v16
	v_add_f32_e64 v17, v89, v17
	v_add_f32_e64 v16, v208, v16
	v_add_f32_e64 v17, v209, v17
	v_pk_add_f32 v[16:17], v[210:211], v[16:17]
	s_waitcnt lgkmcnt(10)
	v_mfma_f32_32x32x16_bf16 v[50:65], v[238:241], v[98:101], v[50:65]
	ds_read_b64_tr_b16 v[238:239], v2 offset:32960
	ds_read_b64_tr_b16 v[240:241], v2 offset:35520
	s_waitcnt lgkmcnt(10)
	v_mfma_f32_32x32x16_bf16 v[34:49], v[246:249], v[98:101], v[34:49]
	v_exp_f32_e32 v200, v90
	v_exp_f32_e32 v201, v91
	v_pk_add_f32 v[90:91], v[96:97], v[158:159] op_sel_hi:[1,0] neg_lo:[0,1] neg_hi:[0,1]
	v_exp_f32_e32 v202, v90
	v_exp_f32_e32 v203, v91
	v_cvt_pk_bf16_f32 v90, v208, v209
	s_waitcnt lgkmcnt(8)
	v_mfma_f32_32x32x16_bf16 v[18:33], v[250:253], v[98:101], v[18:33]
	v_cvt_pk_bf16_f32 v91, v210, v211
	v_cvt_pk_bf16_f32 v92, v200, v201
	v_cvt_pk_bf16_f32 v93, v202, v203
	v_pk_add_f32 v[16:17], v[200:201], v[16:17]
	s_nop 0
	v_pk_add_f32 v[16:17], v[202:203], v[16:17]
	s_waitcnt lgkmcnt(6)
	v_mfma_f32_32x32x16_bf16 v[66:81], v[226:229], v[90:93], v[66:81]
	v_add_f32_e32 v2, v16, v17
	v_add_f32_e32 v153, v153, v2
	s_waitcnt lgkmcnt(4)
	v_mfma_f32_32x32x16_bf16 v[50:65], v[230:233], v[90:93], v[50:65]
	s_waitcnt lgkmcnt(2)
	v_mfma_f32_32x32x16_bf16 v[34:49], v[234:237], v[90:93], v[34:49]
	s_waitcnt lgkmcnt(0)
	v_mfma_f32_32x32x16_bf16 v[18:33], v[238:241], v[90:93], v[18:33]

.LBB0_1321:
	v_lshl_add_u64 v[4:5], v[164:165], 0, s[26:27]
	v_lshl_add_u64 v[8:9], v[166:167], 0, s[26:27]
	v_lshl_add_u64 v[12:13], v[160:161], 0, s[26:27]
	v_lshl_add_u64 v[16:17], v[162:163], 0, s[26:27]
	global_load_dwordx4 v[4:7], v[4:5], off
	v_cndmask_b32_e64 v2, 0, 1, s[20:21]
	global_load_dwordx4 v[8:11], v[8:9], off
	v_cmp_ne_u32_e64 s[18:19], 1, v2
	global_load_dwordx4 v[12:15], v[12:13], off
	s_andn2_b64 vcc, exec, s[20:21]
	global_load_dwordx4 v[146:149], v[16:17], off
	s_cbranch_vccnz .LBB0_1320
	s_bitcmp1_b32 s7, 0
	s_cselect_b32 s8, 0x9400, 0
	s_add_i32 s8, s8, 0
	v_add3_u32 v2, s8, v214, v159
	ds_read_b128 v[226:229], v2
	ds_read_b128 v[230:233], v2 offset:32
	ds_read_b128 v[234:237], v2 offset:64
	ds_read_b128 v[238:241], v2 offset:96
	ds_read_b128 v[246:249], v2 offset:128
	ds_read_b128 v[250:253], v2 offset:160
	s_waitcnt lgkmcnt(5)
	v_mfma_f32_32x32x16_bf16 v[98:113], v[226:229], v[142:145], 0
	ds_read_b128 v[226:229], v2 offset:192
	s_waitcnt lgkmcnt(5)
	v_mfma_f32_32x32x16_bf16 v[98:113], v[230:233], v[138:141], v[98:113]
	ds_read_b128 v[230:233], v2 offset:224
	s_waitcnt lgkmcnt(5)
	v_mfma_f32_32x32x16_bf16 v[98:113], v[234:237], v[134:137], v[98:113]
	ds_read_b128 v[234:237], v2 offset:8704
	s_waitcnt lgkmcnt(5)
	v_mfma_f32_32x32x16_bf16 v[98:113], v[238:241], v[130:133], v[98:113]
	ds_read_b128 v[238:241], v2 offset:8736
	s_waitcnt lgkmcnt(5)
	v_mfma_f32_32x32x16_bf16 v[98:113], v[246:249], v[126:129], v[98:113]
	ds_read_b128 v[246:249], v2 offset:8768
	s_waitcnt lgkmcnt(5)
	v_mfma_f32_32x32x16_bf16 v[98:113], v[250:253], v[122:125], v[98:113]
	ds_read_b128 v[250:253], v2 offset:8800
	s_waitcnt lgkmcnt(5)
	v_mfma_f32_32x32x16_bf16 v[98:113], v[226:229], v[118:121], v[98:113]
	ds_read_b128 v[226:229], v2 offset:8832
	s_waitcnt lgkmcnt(5)
	v_mfma_f32_32x32x16_bf16 v[98:113], v[230:233], v[114:117], v[98:113]
	ds_read_b128 v[230:233], v2 offset:8864
	s_waitcnt lgkmcnt(5)
	v_mfma_f32_32x32x16_bf16 v[82:97], v[234:237], v[142:145], 0
	ds_read_b128 v[234:237], v2 offset:8896
	s_waitcnt lgkmcnt(5)
	v_mfma_f32_32x32x16_bf16 v[82:97], v[238:241], v[138:141], v[82:97]
	ds_read_b128 v[238:241], v2 offset:8928
	s_waitcnt lgkmcnt(5)
	v_mfma_f32_32x32x16_bf16 v[82:97], v[246:249], v[134:137], v[82:97]
	s_waitcnt lgkmcnt(4)
	v_mfma_f32_32x32x16_bf16 v[82:97], v[250:253], v[130:133], v[82:97]
	s_waitcnt lgkmcnt(3)
	v_mfma_f32_32x32x16_bf16 v[82:97], v[226:229], v[126:129], v[82:97]
	s_waitcnt lgkmcnt(2)
	v_mfma_f32_32x32x16_bf16 v[82:97], v[230:233], v[122:125], v[82:97]
	v_max3_f32 v2, v98, v99, v100
	v_max3_f32 v2, v2, v101, v102
	v_max3_f32 v2, v2, v103, v104
	v_max3_f32 v2, v2, v105, v106
	v_max3_f32 v2, v2, v107, v108
	v_max3_f32 v2, v2, v109, v110
	s_waitcnt lgkmcnt(1)
	v_mfma_f32_32x32x16_bf16 v[82:97], v[234:237], v[118:121], v[82:97]
	v_max3_f32 v2, v2, v111, v112
	s_waitcnt lgkmcnt(0)
	v_mfma_f32_32x32x16_bf16 v[82:97], v[238:241], v[114:117], v[82:97]
	s_nop 11
	v_max_f32_e32 v16, v83, v83
	v_max_f32_e32 v17, v82, v82
	v_max_f32_e32 v16, v17, v16
	v_max3_f32 v16, v16, v84, v85
	v_max3_f32 v16, v16, v86, v87
	v_max3_f32 v16, v16, v88, v89
	v_max3_f32 v16, v16, v90, v91
	v_max3_f32 v16, v16, v92, v93
	v_max3_f32 v16, v16, v94, v95
	v_max3_f32 v16, v16, v96, v97
	v_max3_f32 v2, v2, v113, v16
	v_mov_b32_e32 v16, v2
	s_nop 1
	v_permlane32_swap_b32_e32 v2, v16
	v_max_f32_e32 v16, v16, v16
	v_max_f32_e32 v2, v2, v2
	v_max_f32_e32 v2, v2, v16
	v_add_f32_e32 v16, 0x41a00000, v158
	v_cmp_gt_f32_e32 vcc, v2, v16
	s_cbranch_vccz .LBB0_1319
	v_max_f32_e32 v2, v2, v2
	v_max_f32_e32 v16, v158, v158
	v_max_f32_e32 v16, v16, v2
	v_sub_f32_e32 v2, v158, v16
	v_exp_f32_e32 v2, v2
	v_mov_b32_e32 v158, v16
	v_pk_mul_f32 v[80:81], v[80:81], v[2:3] op_sel_hi:[1,0]
	v_pk_mul_f32 v[78:79], v[78:79], v[2:3] op_sel_hi:[1,0]
	v_pk_mul_f32 v[76:77], v[76:77], v[2:3] op_sel_hi:[1,0]
	v_pk_mul_f32 v[74:75], v[74:75], v[2:3] op_sel_hi:[1,0]
	v_pk_mul_f32 v[72:73], v[72:73], v[2:3] op_sel_hi:[1,0]
	v_pk_mul_f32 v[70:71], v[70:71], v[2:3] op_sel_hi:[1,0]
	v_pk_mul_f32 v[68:69], v[68:69], v[2:3] op_sel_hi:[1,0]
	v_pk_mul_f32 v[66:67], v[66:67], v[2:3] op_sel_hi:[1,0]
	v_pk_mul_f32 v[64:65], v[64:65], v[2:3] op_sel_hi:[1,0]
	v_pk_mul_f32 v[62:63], v[62:63], v[2:3] op_sel_hi:[1,0]
	v_pk_mul_f32 v[60:61], v[60:61], v[2:3] op_sel_hi:[1,0]
	v_pk_mul_f32 v[58:59], v[58:59], v[2:3] op_sel_hi:[1,0]
	v_pk_mul_f32 v[56:57], v[56:57], v[2:3] op_sel_hi:[1,0]
	v_pk_mul_f32 v[54:55], v[54:55], v[2:3] op_sel_hi:[1,0]
	v_pk_mul_f32 v[52:53], v[52:53], v[2:3] op_sel_hi:[1,0]
	v_pk_mul_f32 v[50:51], v[50:51], v[2:3] op_sel_hi:[1,0]
	v_pk_mul_f32 v[48:49], v[48:49], v[2:3] op_sel_hi:[1,0]
	v_pk_mul_f32 v[46:47], v[46:47], v[2:3] op_sel_hi:[1,0]
	v_pk_mul_f32 v[44:45], v[44:45], v[2:3] op_sel_hi:[1,0]
	v_pk_mul_f32 v[42:43], v[42:43], v[2:3] op_sel_hi:[1,0]
	v_pk_mul_f32 v[40:41], v[40:41], v[2:3] op_sel_hi:[1,0]
	v_pk_mul_f32 v[38:39], v[38:39], v[2:3] op_sel_hi:[1,0]
	v_pk_mul_f32 v[36:37], v[36:37], v[2:3] op_sel_hi:[1,0]
	v_pk_mul_f32 v[34:35], v[34:35], v[2:3] op_sel_hi:[1,0]
	v_pk_mul_f32 v[32:33], v[32:33], v[2:3] op_sel_hi:[1,0]
	v_pk_mul_f32 v[30:31], v[30:31], v[2:3] op_sel_hi:[1,0]
	v_pk_mul_f32 v[28:29], v[28:29], v[2:3] op_sel_hi:[1,0]
	v_pk_mul_f32 v[26:27], v[26:27], v[2:3] op_sel_hi:[1,0]
	v_pk_mul_f32 v[24:25], v[24:25], v[2:3] op_sel_hi:[1,0]
	v_pk_mul_f32 v[22:23], v[22:23], v[2:3] op_sel_hi:[1,0]
	v_pk_mul_f32 v[20:21], v[20:21], v[2:3] op_sel_hi:[1,0]
	v_pk_mul_f32 v[18:19], v[18:19], v[2:3] op_sel_hi:[1,0]
	v_mul_f32_e32 v153, v153, v2
	s_branch .LBB0_1319

.LBB0_1327:
	v_pk_add_f32 v[4:5], v[98:99], v[158:159] op_sel_hi:[1,0] neg_lo:[0,1] neg_hi:[0,1]
	v_add3_u32 v2, 0, v157, v170
	v_add_u32_e32 v243, 0xd800, v2
	ds_read_b64_tr_b16 v[226:227], v2 offset:55296
	ds_read_b64_tr_b16 v[228:229], v2 offset:57856
	ds_read_b64_tr_b16 v[230:231], v2 offset:55360
	ds_read_b64_tr_b16 v[232:233], v2 offset:57920
	ds_read_b64_tr_b16 v[234:235], v2 offset:55424
	ds_read_b64_tr_b16 v[236:237], v2 offset:57984
	ds_read_b64_tr_b16 v[238:239], v2 offset:55488
	ds_read_b64_tr_b16 v[240:241], v2 offset:58048
	ds_read_b64_tr_b16 v[246:247], v2 offset:60416
	ds_read_b64_tr_b16 v[248:249], v2 offset:62976
	ds_read_b64_tr_b16 v[250:251], v2 offset:60480
	ds_read_b64_tr_b16 v[252:253], v2 offset:63040
	v_exp_f32_e32 v8, v4
	v_exp_f32_e32 v9, v5
	v_pk_add_f32 v[4:5], v[100:101], v[158:159] op_sel_hi:[1,0] neg_lo:[0,1] neg_hi:[0,1]
	v_exp_f32_e32 v10, v4
	v_exp_f32_e32 v11, v5
	v_pk_add_f32 v[4:5], v[102:103], v[158:159] op_sel_hi:[1,0] neg_lo:[0,1] neg_hi:[0,1]
	v_pk_add_f32 v[16:17], v[106:107], v[158:159] op_sel_hi:[1,0] neg_lo:[0,1] neg_hi:[0,1]
	v_exp_f32_e32 v12, v4
	v_exp_f32_e32 v13, v5
	v_pk_add_f32 v[4:5], v[104:105], v[158:159] op_sel_hi:[1,0] neg_lo:[0,1] neg_hi:[0,1]
	v_exp_f32_e32 v14, v4
	v_exp_f32_e32 v15, v5
	v_cvt_pk_bf16_f32 v4, v8, v9
	v_cvt_pk_bf16_f32 v5, v10, v11
	v_cvt_pk_bf16_f32 v6, v12, v13
	v_cvt_pk_bf16_f32 v7, v14, v15
	v_exp_f32_e32 v16, v16
	v_exp_f32_e32 v17, v17
	s_waitcnt lgkmcnt(10)
	v_mfma_f32_32x32x16_bf16 v[66:81], v[226:229], v[4:7], v[66:81]
	ds_read_b64_tr_b16 v[226:227], v2 offset:60544
	ds_read_b64_tr_b16 v[228:229], v2 offset:63104
	v_add_f32_e64 v98, v108, -v158
	v_add_f32_e64 v99, v109, -v158
	v_add_f32_e64 v100, v110, -v158
	v_add_f32_e64 v101, v111, -v158
	v_exp_f32_e32 v98, v98
	v_exp_f32_e32 v99, v99
	v_exp_f32_e32 v100, v100
	v_exp_f32_e32 v101, v101
	v_pk_add_f32 v[8:9], v[8:9], 0 op_sel_hi:[1,0]
	s_waitcnt lgkmcnt(10)
	v_mfma_f32_32x32x16_bf16 v[50:65], v[230:233], v[4:7], v[50:65]
	ds_read_b64_tr_b16 v[230:231], v2 offset:60608
	ds_read_b64_tr_b16 v[232:233], v2 offset:63168
	v_add_f32_e64 v102, v112, -v158
	v_add_f32_e64 v103, v113, -v158
	v_cvt_pk_bf16_f32 v104, v16, v17
	v_exp_f32_e32 v102, v102
	v_exp_f32_e32 v103, v103
	v_cvt_pk_bf16_f32 v105, v98, v99
	v_cvt_pk_bf16_f32 v106, v100, v101
	v_pk_add_f32 v[90:91], v[90:91], v[158:159] op_sel_hi:[1,0] neg_lo:[0,1] neg_hi:[0,1]
	s_waitcnt lgkmcnt(10)
	v_mfma_f32_32x32x16_bf16 v[34:49], v[234:237], v[4:7], v[34:49]
	ds_read_b64_tr_b16 v[234:235], v243 offset:10240
	ds_read_b64_tr_b16 v[236:237], v243 offset:12800
	v_cvt_pk_bf16_f32 v107, v102, v103
	v_add_f32_e64 v8, v10, v8
	v_add_f32_e64 v9, v11, v9
	v_add_f32_e64 v8, v12, v8
	v_add_f32_e64 v9, v13, v9
	v_pk_add_f32 v[8:9], v[14:15], v[8:9]
	s_waitcnt lgkmcnt(10)
	v_mfma_f32_32x32x16_bf16 v[18:33], v[238:241], v[4:7], v[18:33]
	ds_read_b64_tr_b16 v[238:239], v243 offset:10304
	ds_read_b64_tr_b16 v[240:241], v243 offset:12864
	v_exp_f32_e32 v120, v90
	v_exp_f32_e32 v121, v91
	v_pk_add_f32 v[90:91], v[92:93], v[158:159] op_sel_hi:[1,0] neg_lo:[0,1] neg_hi:[0,1]
	v_pk_add_f32 v[8:9], v[16:17], v[8:9]
	s_waitcnt lgkmcnt(10)
	v_mfma_f32_32x32x16_bf16 v[66:81], v[246:249], v[104:107], v[66:81]
	ds_read_b64_tr_b16 v[246:247], v243 offset:10368
	ds_read_b64_tr_b16 v[248:249], v243 offset:12928
	v_add_f32_e64 v4, v82, -v158
	v_add_f32_e64 v5, v83, -v158
	v_add_f32_e64 v6, v84, -v158
	v_add_f32_e64 v7, v85, -v158
	v_add_f32_e64 v82, v86, -v158
	v_add_f32_e64 v83, v87, -v158
	v_pk_add_f32 v[84:85], v[88:89], v[158:159] op_sel_hi:[1,0] neg_lo:[0,1] neg_hi:[0,1]
	v_exp_f32_e32 v4, v4
	v_exp_f32_e32 v5, v5
	v_exp_f32_e32 v6, v6
	s_waitcnt lgkmcnt(10)
	v_mfma_f32_32x32x16_bf16 v[50:65], v[250:253], v[104:107], v[50:65]
	ds_read_b64_tr_b16 v[250:251], v243 offset:10432
	ds_read_b64_tr_b16 v[252:253], v243 offset:12992
	v_exp_f32_e32 v7, v7
	v_exp_f32_e32 v82, v82
	v_exp_f32_e32 v83, v83
	v_exp_f32_e32 v84, v84
	v_exp_f32_e32 v85, v85
	v_cvt_pk_bf16_f32 v86, v4, v5
	v_cvt_pk_bf16_f32 v87, v6, v7
	s_waitcnt lgkmcnt(10)
	v_mfma_f32_32x32x16_bf16 v[34:49], v[226:229], v[104:107], v[34:49]
	ds_read_b64_tr_b16 v[226:227], v243 offset:15360
	ds_read_b64_tr_b16 v[228:229], v243 offset:17920
	v_cvt_pk_bf16_f32 v88, v82, v83
	v_cvt_pk_bf16_f32 v89, v84, v85
	v_exp_f32_e32 v122, v90
	v_exp_f32_e32 v123, v91
	v_pk_add_f32 v[90:91], v[94:95], v[158:159] op_sel_hi:[1,0] neg_lo:[0,1] neg_hi:[0,1]
	v_pk_add_f32 v[8:9], v[98:99], v[8:9]
	s_waitcnt lgkmcnt(10)
	v_mfma_f32_32x32x16_bf16 v[18:33], v[230:233], v[104:107], v[18:33]
	ds_read_b64_tr_b16 v[230:231], v243 offset:15424
	ds_read_b64_tr_b16 v[232:233], v243 offset:17984
	v_pk_add_f32 v[8:9], v[100:101], v[8:9]
	s_nop 0
	v_pk_add_f32 v[8:9], v[102:103], v[8:9]
	s_nop 0
	v_pk_add_f32 v[4:5], v[4:5], v[8:9]
	s_waitcnt lgkmcnt(10)
	v_mfma_f32_32x32x16_bf16 v[66:81], v[234:237], v[86:89], v[66:81]
	ds_read_b64_tr_b16 v[234:235], v243 offset:15488
	ds_read_b64_tr_b16 v[236:237], v243 offset:18048
	v_add_f32_e64 v4, v6, v4
	v_add_f32_e64 v5, v7, v5
	v_add_f32_e64 v4, v82, v4
	v_add_f32_e64 v5, v83, v5
	v_add_f32_e64 v4, v84, v4
	v_add_f32_e64 v5, v85, v5
	v_pk_add_f32 v[4:5], v[120:121], v[4:5]
	s_waitcnt lgkmcnt(10)
	v_mfma_f32_32x32x16_bf16 v[50:65], v[238:241], v[86:89], v[50:65]
	ds_read_b64_tr_b16 v[238:239], v243 offset:15552
	ds_read_b64_tr_b16 v[240:241], v243 offset:18112
	v_add_f32_e64 v4, v122, v4
	v_add_f32_e64 v5, v123, v5
	s_waitcnt lgkmcnt(10)
	v_mfma_f32_32x32x16_bf16 v[34:49], v[246:249], v[86:89], v[34:49]
	v_exp_f32_e32 v112, v90
	v_exp_f32_e32 v113, v91
	v_pk_add_f32 v[90:91], v[96:97], v[158:159] op_sel_hi:[1,0] neg_lo:[0,1] neg_hi:[0,1]
	v_pk_add_f32 v[4:5], v[112:113], v[4:5]
	v_exp_f32_e32 v114, v90
	s_waitcnt lgkmcnt(8)
	v_mfma_f32_32x32x16_bf16 v[18:33], v[250:253], v[86:89], v[18:33]
	v_exp_f32_e32 v115, v91
	v_cvt_pk_bf16_f32 v86, v120, v121
	v_cvt_pk_bf16_f32 v87, v122, v123
	v_cvt_pk_bf16_f32 v88, v112, v113
	v_cvt_pk_bf16_f32 v89, v114, v115
	v_pk_add_f32 v[4:5], v[114:115], v[4:5]
	s_waitcnt lgkmcnt(6)
	v_mfma_f32_32x32x16_bf16 v[66:81], v[226:229], v[86:89], v[66:81]
	v_add_f32_e32 v2, v4, v5
	v_add_f32_e32 v153, v153, v2
	s_waitcnt lgkmcnt(4)
	v_mfma_f32_32x32x16_bf16 v[50:65], v[230:233], v[86:89], v[50:65]
	s_waitcnt lgkmcnt(2)
	v_mfma_f32_32x32x16_bf16 v[34:49], v[234:237], v[86:89], v[34:49]
	s_waitcnt lgkmcnt(0)
	v_mfma_f32_32x32x16_bf16 v[18:33], v[238:241], v[86:89], v[18:33]
